# GEMM main loops: each accumulator's two K-half MFMAs issued back to back (bit-identical accumulation order)
# speedup vs baseline: 1.0218x; 1.0097x over previous
.LBB0_178:
	s_add_u32 s26, s22, 0xfffc0080
	s_addc_u32 s27, s23, -1
	s_add_i32 s34, 0, 0x10000
	s_cmp_eq_u32 s59, 12
	s_cselect_b32 s31, s9, s27
	s_cselect_b32 s30, s15, s26
	s_cselect_b32 s27, s13, s58
	s_cselect_b32 s26, s56, s57
	s_add_i32 s35, 0, 0x14000
	v_add_u32_e32 v140, s34, v195
	v_add_u32_e32 v166, s35, v195
	ds_read_b128 v[128:131], v140
	ds_read_b128 v[132:135], v140 offset:1024
	ds_read_b128 v[136:139], v140 offset:2048
	ds_read_b128 v[140:143], v140 offset:3072
	ds_read_b128 v[144:147], v166
	ds_read_b128 v[148:151], v166 offset:1024
	ds_read_b128 v[180:183], v166 offset:2048
	ds_read_b128 v[184:187], v166 offset:3072
	v_lshl_add_u64 v[166:167], s[22:23], 0, v[160:161]
	s_add_i32 m0, s49, 0xc000
	ds_read_b128 v[188:191], v200
	ds_read_b128 v[202:205], v200 offset:1024
	ds_read_b128 v[206:209], v200 offset:2048
	ds_read_b128 v[210:213], v200 offset:3072
	ds_read_b128 v[228:231], v200 offset:4096
	ds_read_b128 v[232:235], v200 offset:5120
	ds_read_b128 v[236:239], v200 offset:6144
	ds_read_b128 v[240:243], v200 offset:7168
	global_load_lds_dwordx4 v[166:167], off
	v_lshl_add_u64 v[166:167], s[22:23], 0, v[162:163]
	s_add_i32 m0, s49, 0xe000
	s_nop 0
	global_load_lds_dwordx4 v[166:167], off
	s_waitcnt vmcnt(8)
	s_waitcnt lgkmcnt(0)
	s_barrier
	s_setprio 1
	s_waitcnt lgkmcnt(0)
	v_mfma_f32_16x16x32_bf16 v[124:127], v[128:131], v[188:191], v[124:127]
	v_mfma_f32_16x16x32_bf16 v[124:127], v[132:135], v[202:205], v[124:127]
	v_mfma_f32_16x16x32_bf16 v[120:123], v[136:139], v[188:191], v[120:123]
	v_mfma_f32_16x16x32_bf16 v[120:123], v[140:143], v[202:205], v[120:123]
	v_mfma_f32_16x16x32_bf16 v[112:115], v[128:131], v[206:209], v[112:115]
	v_mfma_f32_16x16x32_bf16 v[112:115], v[132:135], v[210:213], v[112:115]
	v_mfma_f32_16x16x32_bf16 v[104:107], v[136:139], v[206:209], v[104:107]
	v_mfma_f32_16x16x32_bf16 v[104:107], v[140:143], v[210:213], v[104:107]
	v_mfma_f32_16x16x32_bf16 v[96:99], v[128:131], v[228:231], v[96:99]
	v_mfma_f32_16x16x32_bf16 v[96:99], v[132:135], v[232:235], v[96:99]
	v_mfma_f32_16x16x32_bf16 v[88:91], v[136:139], v[228:231], v[88:91]
	v_mfma_f32_16x16x32_bf16 v[88:91], v[140:143], v[232:235], v[88:91]
	v_mfma_f32_16x16x32_bf16 v[80:83], v[128:131], v[236:239], v[80:83]
	v_mfma_f32_16x16x32_bf16 v[80:83], v[132:135], v[240:243], v[80:83]
	v_mfma_f32_16x16x32_bf16 v[72:75], v[136:139], v[236:239], v[72:75]
	v_mfma_f32_16x16x32_bf16 v[72:75], v[140:143], v[240:243], v[72:75]
	s_setprio 0
	s_setprio 1
	v_mfma_f32_16x16x32_bf16 v[116:119], v[144:147], v[188:191], v[116:119]
	v_mfma_f32_16x16x32_bf16 v[116:119], v[148:151], v[202:205], v[116:119]
	v_mfma_f32_16x16x32_bf16 v[108:111], v[180:183], v[188:191], v[108:111]
	v_mfma_f32_16x16x32_bf16 v[108:111], v[184:187], v[202:205], v[108:111]
	v_mfma_f32_16x16x32_bf16 v[100:103], v[144:147], v[206:209], v[100:103]
	v_mfma_f32_16x16x32_bf16 v[100:103], v[148:151], v[210:213], v[100:103]
	v_mfma_f32_16x16x32_bf16 v[92:95], v[180:183], v[206:209], v[92:95]
	v_mfma_f32_16x16x32_bf16 v[92:95], v[184:187], v[210:213], v[92:95]
	v_mfma_f32_16x16x32_bf16 v[84:87], v[144:147], v[228:231], v[84:87]
	v_mfma_f32_16x16x32_bf16 v[84:87], v[148:151], v[232:235], v[84:87]
	v_mfma_f32_16x16x32_bf16 v[76:79], v[180:183], v[228:231], v[76:79]
	v_mfma_f32_16x16x32_bf16 v[76:79], v[184:187], v[232:235], v[76:79]
	v_mfma_f32_16x16x32_bf16 v[68:71], v[144:147], v[236:239], v[68:71]
	v_mfma_f32_16x16x32_bf16 v[68:71], v[148:151], v[240:243], v[68:71]
	v_mfma_f32_16x16x32_bf16 v[64:67], v[180:183], v[236:239], v[64:67]
	v_mfma_f32_16x16x32_bf16 v[64:67], v[184:187], v[240:243], v[64:67]
	s_setprio 0
	s_barrier
	s_add_i32 s34, s34, s45
	v_lshl_add_u64 v[166:167], s[26:27], 0, v[168:169]
	s_mov_b32 m0, s34
	ds_read_b128 v[188:191], v200 offset:16384
	ds_read_b128 v[202:205], v200 offset:17408
	ds_read_b128 v[206:209], v200 offset:18432
	ds_read_b128 v[210:213], v200 offset:19456
	ds_read_b128 v[228:231], v200 offset:20480
	ds_read_b128 v[232:235], v200 offset:21504
	ds_read_b128 v[236:239], v200 offset:22528
	ds_read_b128 v[240:243], v200 offset:23552
	global_load_lds_dwordx4 v[166:167], off
	s_add_i32 m0, s34, 0x2000
	s_add_u32 s36, s26, 0x40000
	v_lshl_add_u64 v[192:193], s[26:27], 0, v[152:153]
	s_addc_u32 s37, s27, 0
	s_add_i32 s34, s35, s45
	global_load_lds_dwordx4 v[192:193], off
	v_lshl_add_u64 v[198:199], s[36:37], 0, v[168:169]
	s_mov_b32 m0, s34
	v_lshl_add_u64 v[214:215], s[30:31], 0, v[154:155]
	global_load_lds_dwordx4 v[198:199], off
	v_lshl_add_u64 v[198:199], s[36:37], 0, v[152:153]
	s_add_i32 m0, s34, 0x2000
	s_nop 0
	global_load_lds_dwordx4 v[198:199], off
	v_lshl_add_u64 v[198:199], s[30:31], 0, v[156:157]
	s_mov_b32 m0, s49
	s_nop 0
	global_load_lds_dwordx4 v[198:199], off
	s_mov_b32 m0, s50
	s_nop 0
	global_load_lds_dwordx4 v[214:215], off
	s_waitcnt vmcnt(8)
	s_waitcnt lgkmcnt(0)
	s_barrier
	s_setprio 1
	s_waitcnt lgkmcnt(0)
	v_mfma_f32_16x16x32_bf16 v[60:63], v[128:131], v[188:191], v[60:63]
	v_mfma_f32_16x16x32_bf16 v[60:63], v[132:135], v[202:205], v[60:63]
	v_mfma_f32_16x16x32_bf16 v[56:59], v[136:139], v[188:191], v[56:59]
	v_mfma_f32_16x16x32_bf16 v[56:59], v[140:143], v[202:205], v[56:59]
	v_mfma_f32_16x16x32_bf16 v[48:51], v[128:131], v[206:209], v[48:51]
	v_mfma_f32_16x16x32_bf16 v[48:51], v[132:135], v[210:213], v[48:51]
	v_mfma_f32_16x16x32_bf16 v[40:43], v[136:139], v[206:209], v[40:43]
	v_mfma_f32_16x16x32_bf16 v[40:43], v[140:143], v[210:213], v[40:43]
	v_mfma_f32_16x16x32_bf16 v[32:35], v[128:131], v[228:231], v[32:35]
	v_mfma_f32_16x16x32_bf16 v[32:35], v[132:135], v[232:235], v[32:35]
	v_mfma_f32_16x16x32_bf16 v[24:27], v[136:139], v[228:231], v[24:27]
	v_mfma_f32_16x16x32_bf16 v[24:27], v[140:143], v[232:235], v[24:27]
	v_mfma_f32_16x16x32_bf16 v[16:19], v[128:131], v[236:239], v[16:19]
	v_mfma_f32_16x16x32_bf16 v[16:19], v[132:135], v[240:243], v[16:19]
	v_mfma_f32_16x16x32_bf16 v[8:11], v[136:139], v[236:239], v[8:11]
	v_mfma_f32_16x16x32_bf16 v[8:11], v[140:143], v[240:243], v[8:11]
	s_setprio 0
	s_setprio 1
	v_mfma_f32_16x16x32_bf16 v[52:55], v[144:147], v[188:191], v[52:55]
	v_mfma_f32_16x16x32_bf16 v[52:55], v[148:151], v[202:205], v[52:55]
	v_mfma_f32_16x16x32_bf16 v[44:47], v[180:183], v[188:191], v[44:47]
	v_mfma_f32_16x16x32_bf16 v[44:47], v[184:187], v[202:205], v[44:47]
	v_mfma_f32_16x16x32_bf16 v[36:39], v[144:147], v[206:209], v[36:39]
	v_mfma_f32_16x16x32_bf16 v[36:39], v[148:151], v[210:213], v[36:39]
	v_mfma_f32_16x16x32_bf16 v[28:31], v[180:183], v[206:209], v[28:31]
	v_mfma_f32_16x16x32_bf16 v[28:31], v[184:187], v[210:213], v[28:31]
	v_mfma_f32_16x16x32_bf16 v[20:23], v[144:147], v[228:231], v[20:23]
	v_mfma_f32_16x16x32_bf16 v[20:23], v[148:151], v[232:235], v[20:23]
	v_mfma_f32_16x16x32_bf16 v[12:15], v[180:183], v[228:231], v[12:15]
	v_mfma_f32_16x16x32_bf16 v[12:15], v[184:187], v[232:235], v[12:15]
	v_mfma_f32_16x16x32_bf16 v[4:7], v[144:147], v[236:239], v[4:7]
	v_mfma_f32_16x16x32_bf16 v[4:7], v[148:151], v[240:243], v[4:7]
	v_mfma_f32_16x16x32_bf16 v[0:3], v[180:183], v[236:239], v[0:3]
	v_mfma_f32_16x16x32_bf16 v[0:3], v[184:187], v[240:243], v[0:3]
	s_setprio 0
	s_barrier
	s_add_i32 s34, 0, 0x18000
	s_add_i32 s35, 0, 0x1c000
	v_add_u32_e32 v140, s34, v195
	v_add_u32_e32 v184, s35, v195
	ds_read_b128 v[128:131], v140
	ds_read_b128 v[132:135], v140 offset:1024
	ds_read_b128 v[136:139], v140 offset:2048
	ds_read_b128 v[140:143], v140 offset:3072
	ds_read_b128 v[144:147], v184
	ds_read_b128 v[148:151], v184 offset:1024
	ds_read_b128 v[180:183], v184 offset:2048
	ds_read_b128 v[184:187], v184 offset:3072
	s_add_u32 s30, s30, 0x40000
	s_addc_u32 s31, s31, 0
	s_mov_b32 m0, s51
	v_lshl_add_u64 v[244:245], s[30:31], 0, v[156:157]
	ds_read_b128 v[188:191], v200 offset:32768
	ds_read_b128 v[202:205], v200 offset:33792
	ds_read_b128 v[206:209], v200 offset:34816
	ds_read_b128 v[210:213], v200 offset:35840
	ds_read_b128 v[228:231], v200 offset:36864
	ds_read_b128 v[232:235], v200 offset:37888
	ds_read_b128 v[236:239], v200 offset:38912
	ds_read_b128 v[240:243], v200 offset:39936
	global_load_lds_dwordx4 v[244:245], off
	v_lshl_add_u64 v[244:245], s[30:31], 0, v[154:155]
	s_mov_b32 m0, s52
	s_nop 0
	global_load_lds_dwordx4 v[244:245], off
	s_waitcnt vmcnt(8)
	s_waitcnt lgkmcnt(0)
	s_barrier
	s_setprio 1
	s_waitcnt lgkmcnt(0)
	v_mfma_f32_16x16x32_bf16 v[124:127], v[128:131], v[188:191], v[124:127]
	v_mfma_f32_16x16x32_bf16 v[124:127], v[132:135], v[202:205], v[124:127]
	v_mfma_f32_16x16x32_bf16 v[120:123], v[136:139], v[188:191], v[120:123]
	v_mfma_f32_16x16x32_bf16 v[120:123], v[140:143], v[202:205], v[120:123]
	v_mfma_f32_16x16x32_bf16 v[112:115], v[128:131], v[206:209], v[112:115]
	v_mfma_f32_16x16x32_bf16 v[112:115], v[132:135], v[210:213], v[112:115]
	v_mfma_f32_16x16x32_bf16 v[104:107], v[136:139], v[206:209], v[104:107]
	v_mfma_f32_16x16x32_bf16 v[104:107], v[140:143], v[210:213], v[104:107]
	v_mfma_f32_16x16x32_bf16 v[96:99], v[128:131], v[228:231], v[96:99]
	v_mfma_f32_16x16x32_bf16 v[96:99], v[132:135], v[232:235], v[96:99]
	v_mfma_f32_16x16x32_bf16 v[88:91], v[136:139], v[228:231], v[88:91]
	v_mfma_f32_16x16x32_bf16 v[88:91], v[140:143], v[232:235], v[88:91]
	v_mfma_f32_16x16x32_bf16 v[80:83], v[128:131], v[236:239], v[80:83]
	v_mfma_f32_16x16x32_bf16 v[80:83], v[132:135], v[240:243], v[80:83]
	v_mfma_f32_16x16x32_bf16 v[72:75], v[136:139], v[236:239], v[72:75]
	v_mfma_f32_16x16x32_bf16 v[72:75], v[140:143], v[240:243], v[72:75]
	s_setprio 0
	s_setprio 1
	v_mfma_f32_16x16x32_bf16 v[116:119], v[144:147], v[188:191], v[116:119]
	v_mfma_f32_16x16x32_bf16 v[116:119], v[148:151], v[202:205], v[116:119]
	v_mfma_f32_16x16x32_bf16 v[108:111], v[180:183], v[188:191], v[108:111]
	v_mfma_f32_16x16x32_bf16 v[108:111], v[184:187], v[202:205], v[108:111]
	v_mfma_f32_16x16x32_bf16 v[100:103], v[144:147], v[206:209], v[100:103]
	v_mfma_f32_16x16x32_bf16 v[100:103], v[148:151], v[210:213], v[100:103]
	v_mfma_f32_16x16x32_bf16 v[92:95], v[180:183], v[206:209], v[92:95]
	v_mfma_f32_16x16x32_bf16 v[92:95], v[184:187], v[210:213], v[92:95]
	v_mfma_f32_16x16x32_bf16 v[84:87], v[144:147], v[228:231], v[84:87]
	v_mfma_f32_16x16x32_bf16 v[84:87], v[148:151], v[232:235], v[84:87]
	v_mfma_f32_16x16x32_bf16 v[76:79], v[180:183], v[228:231], v[76:79]
	v_mfma_f32_16x16x32_bf16 v[76:79], v[184:187], v[232:235], v[76:79]
	v_mfma_f32_16x16x32_bf16 v[68:71], v[144:147], v[236:239], v[68:71]
	v_mfma_f32_16x16x32_bf16 v[68:71], v[148:151], v[240:243], v[68:71]
	v_mfma_f32_16x16x32_bf16 v[64:67], v[180:183], v[236:239], v[64:67]
	v_mfma_f32_16x16x32_bf16 v[64:67], v[184:187], v[240:243], v[64:67]
	s_setprio 0
	s_barrier
	s_add_i32 s30, s34, s45
	v_lshl_add_u64 v[166:167], v[166:167], 0, s[20:21]
	s_mov_b32 m0, s30
	ds_read_b128 v[188:191], v200 offset:49152
	ds_read_b128 v[202:205], v200 offset:50176
	ds_read_b128 v[206:209], v200 offset:51200
	ds_read_b128 v[210:213], v200 offset:52224
	ds_read_b128 v[228:231], v200 offset:53248
	ds_read_b128 v[232:235], v200 offset:54272
	ds_read_b128 v[236:239], v200 offset:55296
	ds_read_b128 v[240:243], v200 offset:56320
	global_load_lds_dwordx4 v[166:167], off
	s_add_i32 m0, s30, 0x2000
	s_add_u32 s26, s26, 0x40080
	v_lshl_add_u64 v[166:167], v[192:193], 0, s[20:21]
	s_addc_u32 s27, s27, 0
	s_add_i32 s30, s35, s45
	global_load_lds_dwordx4 v[166:167], off
	v_lshl_add_u64 v[166:167], s[26:27], 0, v[168:169]
	s_mov_b32 m0, s30
	s_nop 0
	global_load_lds_dwordx4 v[166:167], off
	v_lshl_add_u64 v[166:167], s[26:27], 0, v[152:153]
	s_add_i32 m0, s30, 0x2000
	s_nop 0
	global_load_lds_dwordx4 v[166:167], off
	v_lshl_add_u64 v[166:167], v[198:199], 0, s[20:21]
	s_mov_b32 m0, s24
	s_nop 0
	global_load_lds_dwordx4 v[166:167], off
	v_lshl_add_u64 v[166:167], v[214:215], 0, s[20:21]
	s_mov_b32 m0, s53
	s_nop 0
	global_load_lds_dwordx4 v[166:167], off
	s_waitcnt vmcnt(8)
	s_waitcnt lgkmcnt(0)
	s_barrier
	s_setprio 1
	s_waitcnt lgkmcnt(0)
	v_mfma_f32_16x16x32_bf16 v[60:63], v[128:131], v[188:191], v[60:63]
	v_mfma_f32_16x16x32_bf16 v[60:63], v[132:135], v[202:205], v[60:63]
	v_mfma_f32_16x16x32_bf16 v[56:59], v[136:139], v[188:191], v[56:59]
	v_mfma_f32_16x16x32_bf16 v[56:59], v[140:143], v[202:205], v[56:59]
	v_mfma_f32_16x16x32_bf16 v[48:51], v[128:131], v[206:209], v[48:51]
	v_mfma_f32_16x16x32_bf16 v[48:51], v[132:135], v[210:213], v[48:51]
	v_mfma_f32_16x16x32_bf16 v[40:43], v[136:139], v[206:209], v[40:43]
	v_mfma_f32_16x16x32_bf16 v[40:43], v[140:143], v[210:213], v[40:43]
	v_mfma_f32_16x16x32_bf16 v[32:35], v[128:131], v[228:231], v[32:35]
	v_mfma_f32_16x16x32_bf16 v[32:35], v[132:135], v[232:235], v[32:35]
	v_mfma_f32_16x16x32_bf16 v[24:27], v[136:139], v[228:231], v[24:27]
	v_mfma_f32_16x16x32_bf16 v[24:27], v[140:143], v[232:235], v[24:27]
	v_mfma_f32_16x16x32_bf16 v[16:19], v[128:131], v[236:239], v[16:19]
	v_mfma_f32_16x16x32_bf16 v[16:19], v[132:135], v[240:243], v[16:19]
	v_mfma_f32_16x16x32_bf16 v[8:11], v[136:139], v[236:239], v[8:11]
	v_mfma_f32_16x16x32_bf16 v[8:11], v[140:143], v[240:243], v[8:11]
	s_setprio 0
	s_setprio 1
	v_mfma_f32_16x16x32_bf16 v[52:55], v[144:147], v[188:191], v[52:55]
	v_mfma_f32_16x16x32_bf16 v[52:55], v[148:151], v[202:205], v[52:55]
	v_mfma_f32_16x16x32_bf16 v[44:47], v[180:183], v[188:191], v[44:47]
	v_mfma_f32_16x16x32_bf16 v[44:47], v[184:187], v[202:205], v[44:47]
	v_mfma_f32_16x16x32_bf16 v[36:39], v[144:147], v[206:209], v[36:39]
	v_mfma_f32_16x16x32_bf16 v[36:39], v[148:151], v[210:213], v[36:39]
	v_mfma_f32_16x16x32_bf16 v[28:31], v[180:183], v[206:209], v[28:31]
	v_mfma_f32_16x16x32_bf16 v[28:31], v[184:187], v[210:213], v[28:31]
	v_mfma_f32_16x16x32_bf16 v[20:23], v[144:147], v[228:231], v[20:23]
	v_mfma_f32_16x16x32_bf16 v[20:23], v[148:151], v[232:235], v[20:23]
	v_mfma_f32_16x16x32_bf16 v[12:15], v[180:183], v[228:231], v[12:15]
	v_mfma_f32_16x16x32_bf16 v[12:15], v[184:187], v[232:235], v[12:15]
	v_mfma_f32_16x16x32_bf16 v[4:7], v[144:147], v[236:239], v[4:7]
	v_mfma_f32_16x16x32_bf16 v[4:7], v[148:151], v[240:243], v[4:7]
	v_mfma_f32_16x16x32_bf16 v[0:3], v[180:183], v[236:239], v[0:3]
	v_mfma_f32_16x16x32_bf16 v[0:3], v[184:187], v[240:243], v[0:3]
	s_setprio 0
	s_barrier
	s_add_i32 s59, s59, 2
	s_add_u32 s22, s22, 0x100
	s_addc_u32 s23, s23, 0
	s_add_u32 s57, s57, 0x100
	s_addc_u32 s58, s58, 0
	s_cmp_gt_u32 s59, 13
	s_cbranch_scc0 .LBB0_178
	s_and_b64 vcc, exec, s[10:11]
	s_cbranch_vccz .LBB0_181
	s_barrier

.LBB0_776:
	s_add_u32 s26, s22, 0xfffc0080
	s_addc_u32 s27, s23, -1
	s_add_i32 s36, 0, 0x10000
	s_cmp_eq_u32 s55, 12
	s_cselect_b32 s31, s15, s27
	s_cselect_b32 s30, s51, s26
	s_cselect_b32 s27, s13, s54
	s_cselect_b32 s26, s52, s53
	s_add_i32 s56, 0, 0x14000
	v_add_u32_e32 v140, s36, v204
	v_add_u32_e32 v156, s56, v204
	ds_read_b128 v[128:131], v140
	ds_read_b128 v[132:135], v140 offset:1024
	ds_read_b128 v[136:139], v140 offset:2048
	ds_read_b128 v[140:143], v140 offset:3072
	ds_read_b128 v[144:147], v156
	ds_read_b128 v[148:151], v156 offset:1024
	ds_read_b128 v[152:155], v156 offset:2048
	ds_read_b128 v[156:159], v156 offset:3072
	v_lshl_add_u64 v[202:203], s[22:23], 0, v[166:167]
	s_add_i32 m0, s42, 0xc000
	ds_read_b128 v[182:185], v206
	ds_read_b128 v[186:189], v206 offset:1024
	ds_read_b128 v[190:193], v206 offset:2048
	ds_read_b128 v[194:197], v206 offset:3072
	ds_read_b128 v[198:201], v206 offset:4096
	ds_read_b128 v[208:211], v206 offset:5120
	ds_read_b128 v[212:215], v206 offset:6144
	ds_read_b128 v[228:231], v206 offset:7168
	global_load_lds_dwordx4 v[202:203], off
	v_lshl_add_u64 v[202:203], s[22:23], 0, v[180:181]
	s_add_i32 m0, s42, 0xe000
	s_nop 0
	global_load_lds_dwordx4 v[202:203], off
	s_waitcnt vmcnt(8)
	s_waitcnt lgkmcnt(0)
	s_barrier
	s_setprio 1
	s_waitcnt lgkmcnt(0)
	v_mfma_f32_16x16x32_bf16 v[124:127], v[128:131], v[182:185], v[124:127]
	v_mfma_f32_16x16x32_bf16 v[124:127], v[132:135], v[186:189], v[124:127]
	v_mfma_f32_16x16x32_bf16 v[120:123], v[136:139], v[182:185], v[120:123]
	v_mfma_f32_16x16x32_bf16 v[120:123], v[140:143], v[186:189], v[120:123]
	v_mfma_f32_16x16x32_bf16 v[108:111], v[128:131], v[190:193], v[108:111]
	v_mfma_f32_16x16x32_bf16 v[108:111], v[132:135], v[194:197], v[108:111]
	v_mfma_f32_16x16x32_bf16 v[104:107], v[136:139], v[190:193], v[104:107]
	v_mfma_f32_16x16x32_bf16 v[104:107], v[140:143], v[194:197], v[104:107]
	v_mfma_f32_16x16x32_bf16 v[92:95], v[128:131], v[198:201], v[92:95]
	v_mfma_f32_16x16x32_bf16 v[92:95], v[132:135], v[208:211], v[92:95]
	v_mfma_f32_16x16x32_bf16 v[88:91], v[136:139], v[198:201], v[88:91]
	v_mfma_f32_16x16x32_bf16 v[88:91], v[140:143], v[208:211], v[88:91]
	v_mfma_f32_16x16x32_bf16 v[76:79], v[128:131], v[212:215], v[76:79]
	v_mfma_f32_16x16x32_bf16 v[76:79], v[132:135], v[228:231], v[76:79]
	v_mfma_f32_16x16x32_bf16 v[72:75], v[136:139], v[212:215], v[72:75]
	v_mfma_f32_16x16x32_bf16 v[72:75], v[140:143], v[228:231], v[72:75]
	s_setprio 0
	s_setprio 1
	v_mfma_f32_16x16x32_bf16 v[116:119], v[144:147], v[182:185], v[116:119]
	v_mfma_f32_16x16x32_bf16 v[116:119], v[148:151], v[186:189], v[116:119]
	v_mfma_f32_16x16x32_bf16 v[112:115], v[152:155], v[182:185], v[112:115]
	v_mfma_f32_16x16x32_bf16 v[112:115], v[156:159], v[186:189], v[112:115]
	v_mfma_f32_16x16x32_bf16 v[100:103], v[144:147], v[190:193], v[100:103]
	v_mfma_f32_16x16x32_bf16 v[100:103], v[148:151], v[194:197], v[100:103]
	v_mfma_f32_16x16x32_bf16 v[96:99], v[152:155], v[190:193], v[96:99]
	v_mfma_f32_16x16x32_bf16 v[96:99], v[156:159], v[194:197], v[96:99]
	v_mfma_f32_16x16x32_bf16 v[84:87], v[144:147], v[198:201], v[84:87]
	v_mfma_f32_16x16x32_bf16 v[84:87], v[148:151], v[208:211], v[84:87]
	v_mfma_f32_16x16x32_bf16 v[80:83], v[152:155], v[198:201], v[80:83]
	v_mfma_f32_16x16x32_bf16 v[80:83], v[156:159], v[208:211], v[80:83]
	v_mfma_f32_16x16x32_bf16 v[68:71], v[144:147], v[212:215], v[68:71]
	v_mfma_f32_16x16x32_bf16 v[68:71], v[148:151], v[228:231], v[68:71]
	v_mfma_f32_16x16x32_bf16 v[64:67], v[152:155], v[212:215], v[64:67]
	v_mfma_f32_16x16x32_bf16 v[64:67], v[156:159], v[228:231], v[64:67]
	s_setprio 0
	s_barrier
	s_add_i32 s36, s36, s35
	v_lshl_add_u64 v[202:203], s[26:27], 0, v[168:169]
	s_mov_b32 m0, s36
	ds_read_b128 v[182:185], v206 offset:16384
	ds_read_b128 v[186:189], v206 offset:17408
	ds_read_b128 v[190:193], v206 offset:18432
	ds_read_b128 v[194:197], v206 offset:19456
	ds_read_b128 v[198:201], v206 offset:20480
	ds_read_b128 v[208:211], v206 offset:21504
	ds_read_b128 v[212:215], v206 offset:22528
	ds_read_b128 v[228:231], v206 offset:23552
	global_load_lds_dwordx4 v[202:203], off
	s_add_i32 m0, s36, 0x2000
	s_add_u32 s36, s26, 0x40000
	v_lshl_add_u64 v[232:233], s[26:27], 0, v[160:161]
	s_addc_u32 s37, s27, 0
	s_add_i32 s56, s56, s35
	global_load_lds_dwordx4 v[232:233], off
	v_lshl_add_u64 v[234:235], s[36:37], 0, v[168:169]
	s_mov_b32 m0, s56
	v_lshl_add_u64 v[236:237], s[30:31], 0, v[162:163]
	global_load_lds_dwordx4 v[234:235], off
	v_lshl_add_u64 v[234:235], s[36:37], 0, v[160:161]
	s_add_i32 m0, s56, 0x2000
	s_nop 0
	global_load_lds_dwordx4 v[234:235], off
	v_lshl_add_u64 v[234:235], s[30:31], 0, v[164:165]
	s_mov_b32 m0, s42
	s_nop 0
	global_load_lds_dwordx4 v[234:235], off
	s_mov_b32 m0, s43
	s_nop 0
	global_load_lds_dwordx4 v[236:237], off
	s_waitcnt vmcnt(8)
	s_waitcnt lgkmcnt(0)
	s_barrier
	s_setprio 1
	s_waitcnt lgkmcnt(0)
	v_mfma_f32_16x16x32_bf16 v[60:63], v[128:131], v[182:185], v[60:63]
	v_mfma_f32_16x16x32_bf16 v[60:63], v[132:135], v[186:189], v[60:63]
	v_mfma_f32_16x16x32_bf16 v[56:59], v[136:139], v[182:185], v[56:59]
	v_mfma_f32_16x16x32_bf16 v[56:59], v[140:143], v[186:189], v[56:59]
	v_mfma_f32_16x16x32_bf16 v[44:47], v[128:131], v[190:193], v[44:47]
	v_mfma_f32_16x16x32_bf16 v[44:47], v[132:135], v[194:197], v[44:47]
	v_mfma_f32_16x16x32_bf16 v[40:43], v[136:139], v[190:193], v[40:43]
	v_mfma_f32_16x16x32_bf16 v[40:43], v[140:143], v[194:197], v[40:43]
	v_mfma_f32_16x16x32_bf16 v[28:31], v[128:131], v[198:201], v[28:31]
	v_mfma_f32_16x16x32_bf16 v[28:31], v[132:135], v[208:211], v[28:31]
	v_mfma_f32_16x16x32_bf16 v[24:27], v[136:139], v[198:201], v[24:27]
	v_mfma_f32_16x16x32_bf16 v[24:27], v[140:143], v[208:211], v[24:27]
	v_mfma_f32_16x16x32_bf16 v[12:15], v[128:131], v[212:215], v[12:15]
	v_mfma_f32_16x16x32_bf16 v[12:15], v[132:135], v[228:231], v[12:15]
	v_mfma_f32_16x16x32_bf16 v[8:11], v[136:139], v[212:215], v[8:11]
	v_mfma_f32_16x16x32_bf16 v[8:11], v[140:143], v[228:231], v[8:11]
	s_setprio 0
	s_setprio 1
	v_mfma_f32_16x16x32_bf16 v[52:55], v[144:147], v[182:185], v[52:55]
	v_mfma_f32_16x16x32_bf16 v[52:55], v[148:151], v[186:189], v[52:55]
	v_mfma_f32_16x16x32_bf16 v[48:51], v[152:155], v[182:185], v[48:51]
	v_mfma_f32_16x16x32_bf16 v[48:51], v[156:159], v[186:189], v[48:51]
	v_mfma_f32_16x16x32_bf16 v[36:39], v[144:147], v[190:193], v[36:39]
	v_mfma_f32_16x16x32_bf16 v[36:39], v[148:151], v[194:197], v[36:39]
	v_mfma_f32_16x16x32_bf16 v[32:35], v[152:155], v[190:193], v[32:35]
	v_mfma_f32_16x16x32_bf16 v[32:35], v[156:159], v[194:197], v[32:35]
	v_mfma_f32_16x16x32_bf16 v[20:23], v[144:147], v[198:201], v[20:23]
	v_mfma_f32_16x16x32_bf16 v[20:23], v[148:151], v[208:211], v[20:23]
	v_mfma_f32_16x16x32_bf16 v[16:19], v[152:155], v[198:201], v[16:19]
	v_mfma_f32_16x16x32_bf16 v[16:19], v[156:159], v[208:211], v[16:19]
	v_mfma_f32_16x16x32_bf16 v[4:7], v[144:147], v[212:215], v[4:7]
	v_mfma_f32_16x16x32_bf16 v[4:7], v[148:151], v[228:231], v[4:7]
	v_mfma_f32_16x16x32_bf16 v[0:3], v[152:155], v[212:215], v[0:3]
	v_mfma_f32_16x16x32_bf16 v[0:3], v[156:159], v[228:231], v[0:3]
	s_setprio 0
	s_barrier
	s_add_i32 s36, 0, 0x18000
	s_add_i32 s37, 0, 0x1c000
	v_add_u32_e32 v140, s36, v204
	v_add_u32_e32 v156, s37, v204
	ds_read_b128 v[128:131], v140
	ds_read_b128 v[132:135], v140 offset:1024
	ds_read_b128 v[136:139], v140 offset:2048
	ds_read_b128 v[140:143], v140 offset:3072
	ds_read_b128 v[144:147], v156
	ds_read_b128 v[148:151], v156 offset:1024
	ds_read_b128 v[152:155], v156 offset:2048
	ds_read_b128 v[156:159], v156 offset:3072
	s_add_u32 s30, s30, 0x40000
	s_addc_u32 s31, s31, 0
	s_mov_b32 m0, s44
	v_lshl_add_u64 v[238:239], s[30:31], 0, v[164:165]
	ds_read_b128 v[182:185], v206 offset:32768
	ds_read_b128 v[186:189], v206 offset:33792
	ds_read_b128 v[190:193], v206 offset:34816
	ds_read_b128 v[194:197], v206 offset:35840
	ds_read_b128 v[198:201], v206 offset:36864
	ds_read_b128 v[208:211], v206 offset:37888
	ds_read_b128 v[212:215], v206 offset:38912
	ds_read_b128 v[228:231], v206 offset:39936
	global_load_lds_dwordx4 v[238:239], off
	v_lshl_add_u64 v[238:239], s[30:31], 0, v[162:163]
	s_mov_b32 m0, s45
	s_nop 0
	global_load_lds_dwordx4 v[238:239], off
	s_waitcnt vmcnt(8)
	s_waitcnt lgkmcnt(0)
	s_barrier
	s_setprio 1
	s_waitcnt lgkmcnt(0)
	v_mfma_f32_16x16x32_bf16 v[124:127], v[128:131], v[182:185], v[124:127]
	v_mfma_f32_16x16x32_bf16 v[124:127], v[132:135], v[186:189], v[124:127]
	v_mfma_f32_16x16x32_bf16 v[120:123], v[136:139], v[182:185], v[120:123]
	v_mfma_f32_16x16x32_bf16 v[120:123], v[140:143], v[186:189], v[120:123]
	v_mfma_f32_16x16x32_bf16 v[108:111], v[128:131], v[190:193], v[108:111]
	v_mfma_f32_16x16x32_bf16 v[108:111], v[132:135], v[194:197], v[108:111]
	v_mfma_f32_16x16x32_bf16 v[104:107], v[136:139], v[190:193], v[104:107]
	v_mfma_f32_16x16x32_bf16 v[104:107], v[140:143], v[194:197], v[104:107]
	v_mfma_f32_16x16x32_bf16 v[92:95], v[128:131], v[198:201], v[92:95]
	v_mfma_f32_16x16x32_bf16 v[92:95], v[132:135], v[208:211], v[92:95]
	v_mfma_f32_16x16x32_bf16 v[88:91], v[136:139], v[198:201], v[88:91]
	v_mfma_f32_16x16x32_bf16 v[88:91], v[140:143], v[208:211], v[88:91]
	v_mfma_f32_16x16x32_bf16 v[76:79], v[128:131], v[212:215], v[76:79]
	v_mfma_f32_16x16x32_bf16 v[76:79], v[132:135], v[228:231], v[76:79]
	v_mfma_f32_16x16x32_bf16 v[72:75], v[136:139], v[212:215], v[72:75]
	v_mfma_f32_16x16x32_bf16 v[72:75], v[140:143], v[228:231], v[72:75]
	s_setprio 0
	s_setprio 1
	v_mfma_f32_16x16x32_bf16 v[116:119], v[144:147], v[182:185], v[116:119]
	v_mfma_f32_16x16x32_bf16 v[116:119], v[148:151], v[186:189], v[116:119]
	v_mfma_f32_16x16x32_bf16 v[112:115], v[152:155], v[182:185], v[112:115]
	v_mfma_f32_16x16x32_bf16 v[112:115], v[156:159], v[186:189], v[112:115]
	v_mfma_f32_16x16x32_bf16 v[100:103], v[144:147], v[190:193], v[100:103]
	v_mfma_f32_16x16x32_bf16 v[100:103], v[148:151], v[194:197], v[100:103]
	v_mfma_f32_16x16x32_bf16 v[96:99], v[152:155], v[190:193], v[96:99]
	v_mfma_f32_16x16x32_bf16 v[96:99], v[156:159], v[194:197], v[96:99]
	v_mfma_f32_16x16x32_bf16 v[84:87], v[144:147], v[198:201], v[84:87]
	v_mfma_f32_16x16x32_bf16 v[84:87], v[148:151], v[208:211], v[84:87]
	v_mfma_f32_16x16x32_bf16 v[80:83], v[152:155], v[198:201], v[80:83]
	v_mfma_f32_16x16x32_bf16 v[80:83], v[156:159], v[208:211], v[80:83]
	v_mfma_f32_16x16x32_bf16 v[68:71], v[144:147], v[212:215], v[68:71]
	v_mfma_f32_16x16x32_bf16 v[68:71], v[148:151], v[228:231], v[68:71]
	v_mfma_f32_16x16x32_bf16 v[64:67], v[152:155], v[212:215], v[64:67]
	v_mfma_f32_16x16x32_bf16 v[64:67], v[156:159], v[228:231], v[64:67]
	s_setprio 0
	s_barrier
	s_add_i32 s30, s36, s35
	v_lshl_add_u64 v[202:203], v[202:203], 0, s[20:21]
	s_mov_b32 m0, s30
	ds_read_b128 v[182:185], v206 offset:49152
	ds_read_b128 v[186:189], v206 offset:50176
	ds_read_b128 v[190:193], v206 offset:51200
	ds_read_b128 v[194:197], v206 offset:52224
	ds_read_b128 v[198:201], v206 offset:53248
	ds_read_b128 v[208:211], v206 offset:54272
	ds_read_b128 v[212:215], v206 offset:55296
	ds_read_b128 v[228:231], v206 offset:56320
	global_load_lds_dwordx4 v[202:203], off
	s_add_i32 m0, s30, 0x2000
	s_add_u32 s26, s26, 0x40080
	v_lshl_add_u64 v[202:203], v[232:233], 0, s[20:21]
	s_addc_u32 s27, s27, 0
	s_add_i32 s30, s37, s35
	global_load_lds_dwordx4 v[202:203], off
	v_lshl_add_u64 v[202:203], s[26:27], 0, v[168:169]
	s_mov_b32 m0, s30
	s_nop 0
	global_load_lds_dwordx4 v[202:203], off
	v_lshl_add_u64 v[202:203], s[26:27], 0, v[160:161]
	s_add_i32 m0, s30, 0x2000
	s_nop 0
	global_load_lds_dwordx4 v[202:203], off
	v_lshl_add_u64 v[202:203], v[234:235], 0, s[20:21]
	s_mov_b32 m0, s47
	s_nop 0
	global_load_lds_dwordx4 v[202:203], off
	v_lshl_add_u64 v[202:203], v[236:237], 0, s[20:21]
	s_mov_b32 m0, s48
	s_nop 0
	global_load_lds_dwordx4 v[202:203], off
	s_waitcnt vmcnt(8)
	s_waitcnt lgkmcnt(0)
	s_barrier
	s_setprio 1
	s_waitcnt lgkmcnt(0)
	v_mfma_f32_16x16x32_bf16 v[60:63], v[128:131], v[182:185], v[60:63]
	v_mfma_f32_16x16x32_bf16 v[60:63], v[132:135], v[186:189], v[60:63]
	v_mfma_f32_16x16x32_bf16 v[56:59], v[136:139], v[182:185], v[56:59]
	v_mfma_f32_16x16x32_bf16 v[56:59], v[140:143], v[186:189], v[56:59]
	v_mfma_f32_16x16x32_bf16 v[44:47], v[128:131], v[190:193], v[44:47]
	v_mfma_f32_16x16x32_bf16 v[44:47], v[132:135], v[194:197], v[44:47]
	v_mfma_f32_16x16x32_bf16 v[40:43], v[136:139], v[190:193], v[40:43]
	v_mfma_f32_16x16x32_bf16 v[40:43], v[140:143], v[194:197], v[40:43]
	v_mfma_f32_16x16x32_bf16 v[28:31], v[128:131], v[198:201], v[28:31]
	v_mfma_f32_16x16x32_bf16 v[28:31], v[132:135], v[208:211], v[28:31]
	v_mfma_f32_16x16x32_bf16 v[24:27], v[136:139], v[198:201], v[24:27]
	v_mfma_f32_16x16x32_bf16 v[24:27], v[140:143], v[208:211], v[24:27]
	v_mfma_f32_16x16x32_bf16 v[12:15], v[128:131], v[212:215], v[12:15]
	v_mfma_f32_16x16x32_bf16 v[12:15], v[132:135], v[228:231], v[12:15]
	v_mfma_f32_16x16x32_bf16 v[8:11], v[136:139], v[212:215], v[8:11]
	v_mfma_f32_16x16x32_bf16 v[8:11], v[140:143], v[228:231], v[8:11]
	s_setprio 0
	s_setprio 1
	v_mfma_f32_16x16x32_bf16 v[52:55], v[144:147], v[182:185], v[52:55]
	v_mfma_f32_16x16x32_bf16 v[52:55], v[148:151], v[186:189], v[52:55]
	v_mfma_f32_16x16x32_bf16 v[48:51], v[152:155], v[182:185], v[48:51]
	v_mfma_f32_16x16x32_bf16 v[48:51], v[156:159], v[186:189], v[48:51]
	v_mfma_f32_16x16x32_bf16 v[36:39], v[144:147], v[190:193], v[36:39]
	v_mfma_f32_16x16x32_bf16 v[36:39], v[148:151], v[194:197], v[36:39]
	v_mfma_f32_16x16x32_bf16 v[32:35], v[152:155], v[190:193], v[32:35]
	v_mfma_f32_16x16x32_bf16 v[32:35], v[156:159], v[194:197], v[32:35]
	v_mfma_f32_16x16x32_bf16 v[20:23], v[144:147], v[198:201], v[20:23]
	v_mfma_f32_16x16x32_bf16 v[20:23], v[148:151], v[208:211], v[20:23]
	v_mfma_f32_16x16x32_bf16 v[16:19], v[152:155], v[198:201], v[16:19]
	v_mfma_f32_16x16x32_bf16 v[16:19], v[156:159], v[208:211], v[16:19]
	v_mfma_f32_16x16x32_bf16 v[4:7], v[144:147], v[212:215], v[4:7]
	v_mfma_f32_16x16x32_bf16 v[4:7], v[148:151], v[228:231], v[4:7]
	v_mfma_f32_16x16x32_bf16 v[0:3], v[152:155], v[212:215], v[0:3]
	v_mfma_f32_16x16x32_bf16 v[0:3], v[156:159], v[228:231], v[0:3]
	s_setprio 0
	s_barrier
	s_add_i32 s55, s55, 2
	s_add_u32 s22, s22, 0x100
	s_addc_u32 s23, s23, 0
	s_add_u32 s53, s53, 0x100
	s_addc_u32 s54, s54, 0
	s_cmp_gt_u32 s55, 13
	s_cbranch_scc0 .LBB0_776
	s_and_b64 vcc, exec, s[10:11]
	s_cbranch_vccz .LBB0_779
	s_barrier

.LBB0_890:
	s_add_u32 s18, s0, 0xfffc0080
	s_addc_u32 s19, s1, -1
	s_add_i32 s36, 0, 0x10000
	s_cmp_eq_u32 s50, 12
	s_cselect_b32 s23, s13, s19
	s_cselect_b32 s22, s46, s18
	s_cselect_b32 s19, s11, s49
	s_cselect_b32 s18, s47, s48
	s_add_i32 s51, 0, 0x14000
	v_add_u32_e32 v140, s36, v193
	v_add_u32_e32 v180, s51, v193
	ds_read_b128 v[128:131], v140
	ds_read_b128 v[132:135], v140 offset:1024
	ds_read_b128 v[136:139], v140 offset:2048
	ds_read_b128 v[140:143], v140 offset:3072
	ds_read_b128 v[144:147], v180
	ds_read_b128 v[148:151], v180 offset:1024
	ds_read_b128 v[164:167], v180 offset:2048
	ds_read_b128 v[180:183], v180 offset:3072
	v_lshl_add_u64 v[196:197], s[0:1], 0, v[160:161]
	s_add_i32 m0, s30, 0xc000
	ds_read_b128 v[184:187], v198
	ds_read_b128 v[188:191], v198 offset:1024
	ds_read_b128 v[200:203], v198 offset:2048
	ds_read_b128 v[204:207], v198 offset:3072
	ds_read_b128 v[208:211], v198 offset:4096
	ds_read_b128 v[212:215], v198 offset:5120
	ds_read_b128 v[228:231], v198 offset:6144
	ds_read_b128 v[232:235], v198 offset:7168
	global_load_lds_dwordx4 v[196:197], off
	v_lshl_add_u64 v[196:197], s[0:1], 0, v[162:163]
	s_add_i32 m0, s30, 0xe000
	s_nop 0
	global_load_lds_dwordx4 v[196:197], off
	s_waitcnt vmcnt(8)
	s_waitcnt lgkmcnt(0)
	s_barrier
	s_setprio 1
	s_waitcnt lgkmcnt(0)
	v_mfma_f32_16x16x32_bf16 v[124:127], v[128:131], v[184:187], v[124:127]
	v_mfma_f32_16x16x32_bf16 v[124:127], v[132:135], v[188:191], v[124:127]
	v_mfma_f32_16x16x32_bf16 v[120:123], v[136:139], v[184:187], v[120:123]
	v_mfma_f32_16x16x32_bf16 v[120:123], v[140:143], v[188:191], v[120:123]
	v_mfma_f32_16x16x32_bf16 v[108:111], v[128:131], v[200:203], v[108:111]
	v_mfma_f32_16x16x32_bf16 v[108:111], v[132:135], v[204:207], v[108:111]
	v_mfma_f32_16x16x32_bf16 v[104:107], v[136:139], v[200:203], v[104:107]
	v_mfma_f32_16x16x32_bf16 v[104:107], v[140:143], v[204:207], v[104:107]
	v_mfma_f32_16x16x32_bf16 v[92:95], v[128:131], v[208:211], v[92:95]
	v_mfma_f32_16x16x32_bf16 v[92:95], v[132:135], v[212:215], v[92:95]
	v_mfma_f32_16x16x32_bf16 v[88:91], v[136:139], v[208:211], v[88:91]
	v_mfma_f32_16x16x32_bf16 v[88:91], v[140:143], v[212:215], v[88:91]
	v_mfma_f32_16x16x32_bf16 v[76:79], v[128:131], v[228:231], v[76:79]
	v_mfma_f32_16x16x32_bf16 v[76:79], v[132:135], v[232:235], v[76:79]
	v_mfma_f32_16x16x32_bf16 v[72:75], v[136:139], v[228:231], v[72:75]
	v_mfma_f32_16x16x32_bf16 v[72:75], v[140:143], v[232:235], v[72:75]
	s_setprio 0
	s_setprio 1
	v_mfma_f32_16x16x32_bf16 v[116:119], v[144:147], v[184:187], v[116:119]
	v_mfma_f32_16x16x32_bf16 v[116:119], v[148:151], v[188:191], v[116:119]
	v_mfma_f32_16x16x32_bf16 v[112:115], v[164:167], v[184:187], v[112:115]
	v_mfma_f32_16x16x32_bf16 v[112:115], v[180:183], v[188:191], v[112:115]
	v_mfma_f32_16x16x32_bf16 v[100:103], v[144:147], v[200:203], v[100:103]
	v_mfma_f32_16x16x32_bf16 v[100:103], v[148:151], v[204:207], v[100:103]
	v_mfma_f32_16x16x32_bf16 v[96:99], v[164:167], v[200:203], v[96:99]
	v_mfma_f32_16x16x32_bf16 v[96:99], v[180:183], v[204:207], v[96:99]
	v_mfma_f32_16x16x32_bf16 v[84:87], v[144:147], v[208:211], v[84:87]
	v_mfma_f32_16x16x32_bf16 v[84:87], v[148:151], v[212:215], v[84:87]
	v_mfma_f32_16x16x32_bf16 v[80:83], v[164:167], v[208:211], v[80:83]
	v_mfma_f32_16x16x32_bf16 v[80:83], v[180:183], v[212:215], v[80:83]
	v_mfma_f32_16x16x32_bf16 v[68:71], v[144:147], v[228:231], v[68:71]
	v_mfma_f32_16x16x32_bf16 v[68:71], v[148:151], v[232:235], v[68:71]
	v_mfma_f32_16x16x32_bf16 v[64:67], v[164:167], v[228:231], v[64:67]
	v_mfma_f32_16x16x32_bf16 v[64:67], v[180:183], v[232:235], v[64:67]
	s_setprio 0
	s_barrier
	s_add_i32 s36, s36, s27
	v_lshl_add_u64 v[196:197], s[18:19], 0, v[168:169]
	s_mov_b32 m0, s36
	ds_read_b128 v[184:187], v198 offset:16384
	ds_read_b128 v[188:191], v198 offset:17408
	ds_read_b128 v[200:203], v198 offset:18432
	ds_read_b128 v[204:207], v198 offset:19456
	ds_read_b128 v[208:211], v198 offset:20480
	ds_read_b128 v[212:215], v198 offset:21504
	ds_read_b128 v[228:231], v198 offset:22528
	ds_read_b128 v[232:235], v198 offset:23552
	global_load_lds_dwordx4 v[196:197], off
	s_add_i32 m0, s36, 0x2000
	s_add_u32 s36, s18, 0x40000
	v_lshl_add_u64 v[236:237], s[18:19], 0, v[152:153]
	s_addc_u32 s37, s19, 0
	s_add_i32 s51, s51, s27
	global_load_lds_dwordx4 v[236:237], off
	v_lshl_add_u64 v[238:239], s[36:37], 0, v[168:169]
	s_mov_b32 m0, s51
	v_lshl_add_u64 v[240:241], s[22:23], 0, v[154:155]
	global_load_lds_dwordx4 v[238:239], off
	v_lshl_add_u64 v[238:239], s[36:37], 0, v[152:153]
	s_add_i32 m0, s51, 0x2000
	s_nop 0
	global_load_lds_dwordx4 v[238:239], off
	v_lshl_add_u64 v[238:239], s[22:23], 0, v[156:157]
	s_mov_b32 m0, s30
	s_nop 0
	global_load_lds_dwordx4 v[238:239], off
	s_mov_b32 m0, s31
	s_nop 0
	global_load_lds_dwordx4 v[240:241], off
	s_waitcnt vmcnt(8)
	s_waitcnt lgkmcnt(0)
	s_barrier
	s_setprio 1
	s_waitcnt lgkmcnt(0)
	v_mfma_f32_16x16x32_bf16 v[60:63], v[128:131], v[184:187], v[60:63]
	v_mfma_f32_16x16x32_bf16 v[60:63], v[132:135], v[188:191], v[60:63]
	v_mfma_f32_16x16x32_bf16 v[56:59], v[136:139], v[184:187], v[56:59]
	v_mfma_f32_16x16x32_bf16 v[56:59], v[140:143], v[188:191], v[56:59]
	v_mfma_f32_16x16x32_bf16 v[44:47], v[128:131], v[200:203], v[44:47]
	v_mfma_f32_16x16x32_bf16 v[44:47], v[132:135], v[204:207], v[44:47]
	v_mfma_f32_16x16x32_bf16 v[40:43], v[136:139], v[200:203], v[40:43]
	v_mfma_f32_16x16x32_bf16 v[40:43], v[140:143], v[204:207], v[40:43]
	v_mfma_f32_16x16x32_bf16 v[28:31], v[128:131], v[208:211], v[28:31]
	v_mfma_f32_16x16x32_bf16 v[28:31], v[132:135], v[212:215], v[28:31]
	v_mfma_f32_16x16x32_bf16 v[24:27], v[136:139], v[208:211], v[24:27]
	v_mfma_f32_16x16x32_bf16 v[24:27], v[140:143], v[212:215], v[24:27]
	v_mfma_f32_16x16x32_bf16 v[12:15], v[128:131], v[228:231], v[12:15]
	v_mfma_f32_16x16x32_bf16 v[12:15], v[132:135], v[232:235], v[12:15]
	v_mfma_f32_16x16x32_bf16 v[8:11], v[136:139], v[228:231], v[8:11]
	v_mfma_f32_16x16x32_bf16 v[8:11], v[140:143], v[232:235], v[8:11]
	s_setprio 0
	s_setprio 1
	v_mfma_f32_16x16x32_bf16 v[52:55], v[144:147], v[184:187], v[52:55]
	v_mfma_f32_16x16x32_bf16 v[52:55], v[148:151], v[188:191], v[52:55]
	v_mfma_f32_16x16x32_bf16 v[48:51], v[164:167], v[184:187], v[48:51]
	v_mfma_f32_16x16x32_bf16 v[48:51], v[180:183], v[188:191], v[48:51]
	v_mfma_f32_16x16x32_bf16 v[36:39], v[144:147], v[200:203], v[36:39]
	v_mfma_f32_16x16x32_bf16 v[36:39], v[148:151], v[204:207], v[36:39]
	v_mfma_f32_16x16x32_bf16 v[32:35], v[164:167], v[200:203], v[32:35]
	v_mfma_f32_16x16x32_bf16 v[32:35], v[180:183], v[204:207], v[32:35]
	v_mfma_f32_16x16x32_bf16 v[20:23], v[144:147], v[208:211], v[20:23]
	v_mfma_f32_16x16x32_bf16 v[20:23], v[148:151], v[212:215], v[20:23]
	v_mfma_f32_16x16x32_bf16 v[16:19], v[164:167], v[208:211], v[16:19]
	v_mfma_f32_16x16x32_bf16 v[16:19], v[180:183], v[212:215], v[16:19]
	v_mfma_f32_16x16x32_bf16 v[4:7], v[144:147], v[228:231], v[4:7]
	v_mfma_f32_16x16x32_bf16 v[4:7], v[148:151], v[232:235], v[4:7]
	v_mfma_f32_16x16x32_bf16 v[0:3], v[164:167], v[228:231], v[0:3]
	v_mfma_f32_16x16x32_bf16 v[0:3], v[180:183], v[232:235], v[0:3]
	s_setprio 0
	s_barrier
	s_add_i32 s36, 0, 0x18000
	s_add_i32 s37, 0, 0x1c000
	v_add_u32_e32 v140, s36, v193
	v_add_u32_e32 v180, s37, v193
	ds_read_b128 v[128:131], v140
	ds_read_b128 v[132:135], v140 offset:1024
	ds_read_b128 v[136:139], v140 offset:2048
	ds_read_b128 v[140:143], v140 offset:3072
	ds_read_b128 v[144:147], v180
	ds_read_b128 v[148:151], v180 offset:1024
	ds_read_b128 v[164:167], v180 offset:2048
	ds_read_b128 v[180:183], v180 offset:3072
	s_add_u32 s22, s22, 0x40000
	s_addc_u32 s23, s23, 0
	s_mov_b32 m0, s34
	v_lshl_add_u64 v[242:243], s[22:23], 0, v[156:157]
	ds_read_b128 v[184:187], v198 offset:32768
	ds_read_b128 v[188:191], v198 offset:33792
	ds_read_b128 v[200:203], v198 offset:34816
	ds_read_b128 v[204:207], v198 offset:35840
	ds_read_b128 v[208:211], v198 offset:36864
	ds_read_b128 v[212:215], v198 offset:37888
	ds_read_b128 v[228:231], v198 offset:38912
	ds_read_b128 v[232:235], v198 offset:39936
	global_load_lds_dwordx4 v[242:243], off
	v_lshl_add_u64 v[242:243], s[22:23], 0, v[154:155]
	s_mov_b32 m0, s35
	s_nop 0
	global_load_lds_dwordx4 v[242:243], off
	s_waitcnt vmcnt(8)
	s_waitcnt lgkmcnt(0)
	s_barrier
	s_setprio 1
	s_waitcnt lgkmcnt(0)
	v_mfma_f32_16x16x32_bf16 v[124:127], v[128:131], v[184:187], v[124:127]
	v_mfma_f32_16x16x32_bf16 v[124:127], v[132:135], v[188:191], v[124:127]
	v_mfma_f32_16x16x32_bf16 v[120:123], v[136:139], v[184:187], v[120:123]
	v_mfma_f32_16x16x32_bf16 v[120:123], v[140:143], v[188:191], v[120:123]
	v_mfma_f32_16x16x32_bf16 v[108:111], v[128:131], v[200:203], v[108:111]
	v_mfma_f32_16x16x32_bf16 v[108:111], v[132:135], v[204:207], v[108:111]
	v_mfma_f32_16x16x32_bf16 v[104:107], v[136:139], v[200:203], v[104:107]
	v_mfma_f32_16x16x32_bf16 v[104:107], v[140:143], v[204:207], v[104:107]
	v_mfma_f32_16x16x32_bf16 v[92:95], v[128:131], v[208:211], v[92:95]
	v_mfma_f32_16x16x32_bf16 v[92:95], v[132:135], v[212:215], v[92:95]
	v_mfma_f32_16x16x32_bf16 v[88:91], v[136:139], v[208:211], v[88:91]
	v_mfma_f32_16x16x32_bf16 v[88:91], v[140:143], v[212:215], v[88:91]
	v_mfma_f32_16x16x32_bf16 v[76:79], v[128:131], v[228:231], v[76:79]
	v_mfma_f32_16x16x32_bf16 v[76:79], v[132:135], v[232:235], v[76:79]
	v_mfma_f32_16x16x32_bf16 v[72:75], v[136:139], v[228:231], v[72:75]
	v_mfma_f32_16x16x32_bf16 v[72:75], v[140:143], v[232:235], v[72:75]
	s_setprio 0
	s_setprio 1
	v_mfma_f32_16x16x32_bf16 v[116:119], v[144:147], v[184:187], v[116:119]
	v_mfma_f32_16x16x32_bf16 v[116:119], v[148:151], v[188:191], v[116:119]
	v_mfma_f32_16x16x32_bf16 v[112:115], v[164:167], v[184:187], v[112:115]
	v_mfma_f32_16x16x32_bf16 v[112:115], v[180:183], v[188:191], v[112:115]
	v_mfma_f32_16x16x32_bf16 v[100:103], v[144:147], v[200:203], v[100:103]
	v_mfma_f32_16x16x32_bf16 v[100:103], v[148:151], v[204:207], v[100:103]
	v_mfma_f32_16x16x32_bf16 v[96:99], v[164:167], v[200:203], v[96:99]
	v_mfma_f32_16x16x32_bf16 v[96:99], v[180:183], v[204:207], v[96:99]
	v_mfma_f32_16x16x32_bf16 v[84:87], v[144:147], v[208:211], v[84:87]
	v_mfma_f32_16x16x32_bf16 v[84:87], v[148:151], v[212:215], v[84:87]
	v_mfma_f32_16x16x32_bf16 v[80:83], v[164:167], v[208:211], v[80:83]
	v_mfma_f32_16x16x32_bf16 v[80:83], v[180:183], v[212:215], v[80:83]
	v_mfma_f32_16x16x32_bf16 v[68:71], v[144:147], v[228:231], v[68:71]
	v_mfma_f32_16x16x32_bf16 v[68:71], v[148:151], v[232:235], v[68:71]
	v_mfma_f32_16x16x32_bf16 v[64:67], v[164:167], v[228:231], v[64:67]
	v_mfma_f32_16x16x32_bf16 v[64:67], v[180:183], v[232:235], v[64:67]
	s_setprio 0
	s_barrier
	s_add_i32 s22, s36, s27
	v_lshl_add_u64 v[196:197], v[196:197], 0, s[20:21]
	s_mov_b32 m0, s22
	ds_read_b128 v[184:187], v198 offset:49152
	ds_read_b128 v[188:191], v198 offset:50176
	ds_read_b128 v[200:203], v198 offset:51200
	ds_read_b128 v[204:207], v198 offset:52224
	ds_read_b128 v[208:211], v198 offset:53248
	ds_read_b128 v[212:215], v198 offset:54272
	ds_read_b128 v[228:231], v198 offset:55296
	ds_read_b128 v[232:235], v198 offset:56320
	global_load_lds_dwordx4 v[196:197], off
	s_add_i32 m0, s22, 0x2000
	s_add_u32 s18, s18, 0x40080
	v_lshl_add_u64 v[196:197], v[236:237], 0, s[20:21]
	s_addc_u32 s19, s19, 0
	s_add_i32 s22, s37, s27
	global_load_lds_dwordx4 v[196:197], off
	v_lshl_add_u64 v[196:197], s[18:19], 0, v[168:169]
	s_mov_b32 m0, s22
	s_nop 0
	global_load_lds_dwordx4 v[196:197], off
	v_lshl_add_u64 v[196:197], s[18:19], 0, v[152:153]
	s_add_i32 m0, s22, 0x2000
	s_nop 0
	global_load_lds_dwordx4 v[196:197], off
	v_lshl_add_u64 v[196:197], v[238:239], 0, s[20:21]
	s_mov_b32 m0, s24
	s_nop 0
	global_load_lds_dwordx4 v[196:197], off
	v_lshl_add_u64 v[196:197], v[240:241], 0, s[20:21]
	s_mov_b32 m0, s42
	s_nop 0
	global_load_lds_dwordx4 v[196:197], off
	s_waitcnt vmcnt(8)
	s_waitcnt lgkmcnt(0)
	s_barrier
	s_setprio 1
	s_waitcnt lgkmcnt(0)
	v_mfma_f32_16x16x32_bf16 v[60:63], v[128:131], v[184:187], v[60:63]
	v_mfma_f32_16x16x32_bf16 v[60:63], v[132:135], v[188:191], v[60:63]
	v_mfma_f32_16x16x32_bf16 v[56:59], v[136:139], v[184:187], v[56:59]
	v_mfma_f32_16x16x32_bf16 v[56:59], v[140:143], v[188:191], v[56:59]
	v_mfma_f32_16x16x32_bf16 v[44:47], v[128:131], v[200:203], v[44:47]
	v_mfma_f32_16x16x32_bf16 v[44:47], v[132:135], v[204:207], v[44:47]
	v_mfma_f32_16x16x32_bf16 v[40:43], v[136:139], v[200:203], v[40:43]
	v_mfma_f32_16x16x32_bf16 v[40:43], v[140:143], v[204:207], v[40:43]
	v_mfma_f32_16x16x32_bf16 v[28:31], v[128:131], v[208:211], v[28:31]
	v_mfma_f32_16x16x32_bf16 v[28:31], v[132:135], v[212:215], v[28:31]
	v_mfma_f32_16x16x32_bf16 v[24:27], v[136:139], v[208:211], v[24:27]
	v_mfma_f32_16x16x32_bf16 v[24:27], v[140:143], v[212:215], v[24:27]
	v_mfma_f32_16x16x32_bf16 v[12:15], v[128:131], v[228:231], v[12:15]
	v_mfma_f32_16x16x32_bf16 v[12:15], v[132:135], v[232:235], v[12:15]
	v_mfma_f32_16x16x32_bf16 v[8:11], v[136:139], v[228:231], v[8:11]
	v_mfma_f32_16x16x32_bf16 v[8:11], v[140:143], v[232:235], v[8:11]
	s_setprio 0
	s_setprio 1
	v_mfma_f32_16x16x32_bf16 v[52:55], v[144:147], v[184:187], v[52:55]
	v_mfma_f32_16x16x32_bf16 v[52:55], v[148:151], v[188:191], v[52:55]
	v_mfma_f32_16x16x32_bf16 v[48:51], v[164:167], v[184:187], v[48:51]
	v_mfma_f32_16x16x32_bf16 v[48:51], v[180:183], v[188:191], v[48:51]
	v_mfma_f32_16x16x32_bf16 v[36:39], v[144:147], v[200:203], v[36:39]
	v_mfma_f32_16x16x32_bf16 v[36:39], v[148:151], v[204:207], v[36:39]
	v_mfma_f32_16x16x32_bf16 v[32:35], v[164:167], v[200:203], v[32:35]
	v_mfma_f32_16x16x32_bf16 v[32:35], v[180:183], v[204:207], v[32:35]
	v_mfma_f32_16x16x32_bf16 v[20:23], v[144:147], v[208:211], v[20:23]
	v_mfma_f32_16x16x32_bf16 v[20:23], v[148:151], v[212:215], v[20:23]
	v_mfma_f32_16x16x32_bf16 v[16:19], v[164:167], v[208:211], v[16:19]
	v_mfma_f32_16x16x32_bf16 v[16:19], v[180:183], v[212:215], v[16:19]
	v_mfma_f32_16x16x32_bf16 v[4:7], v[144:147], v[228:231], v[4:7]
	v_mfma_f32_16x16x32_bf16 v[4:7], v[148:151], v[232:235], v[4:7]
	v_mfma_f32_16x16x32_bf16 v[0:3], v[164:167], v[228:231], v[0:3]
	v_mfma_f32_16x16x32_bf16 v[0:3], v[180:183], v[232:235], v[0:3]
	s_setprio 0
	s_barrier
	s_add_i32 s50, s50, 2
	s_add_u32 s0, s0, 0x100
	s_addc_u32 s1, s1, 0
	s_add_u32 s48, s48, 0x100
	s_addc_u32 s49, s49, 0
	s_cmp_gt_u32 s50, 13
	s_cbranch_scc0 .LBB0_890
	s_and_b64 vcc, exec, s[8:9]
	s_cbranch_vccz .LBB0_893
	s_barrier

.LBB0_986:
	s_add_u32 s34, s8, 0xfff00080
	s_addc_u32 s35, s9, -1
	s_add_i32 s36, 0, 0x10000
	s_cmp_eq_u32 s57, 60
	s_cselect_b32 s41, s23, s35
	s_cselect_b32 s40, s53, s34
	s_cselect_b32 s35, s19, s56
	s_cselect_b32 s34, s54, s55
	s_add_i32 s58, 0, 0x14000
	v_add_u32_e32 v140, s36, v228
	v_add_u32_e32 v156, s58, v228
	ds_read_b128 v[128:131], v140
	ds_read_b128 v[132:135], v140 offset:1024
	ds_read_b128 v[136:139], v140 offset:2048
	ds_read_b128 v[140:143], v140 offset:3072
	ds_read_b128 v[144:147], v156
	ds_read_b128 v[148:151], v156 offset:1024
	ds_read_b128 v[152:155], v156 offset:2048
	ds_read_b128 v[156:159], v156 offset:3072
	v_lshl_add_u64 v[214:215], s[8:9], 0, v[186:187]
	s_add_i32 m0, s44, 0xc000
	ds_read_b128 v[160:163], v230
	ds_read_b128 v[164:167], v230 offset:1024
	ds_read_b128 v[190:193], v230 offset:2048
	ds_read_b128 v[194:197], v230 offset:3072
	ds_read_b128 v[198:201], v230 offset:4096
	ds_read_b128 v[202:205], v230 offset:5120
	ds_read_b128 v[206:209], v230 offset:6144
	ds_read_b128 v[210:213], v230 offset:7168
	global_load_lds_dwordx4 v[214:215], off
	v_lshl_add_u64 v[214:215], s[8:9], 0, v[188:189]
	s_add_i32 m0, s44, 0xe000
	s_nop 0
	global_load_lds_dwordx4 v[214:215], off
	s_waitcnt vmcnt(8)
	s_waitcnt lgkmcnt(0)
	s_barrier
	s_setprio 1
	s_waitcnt lgkmcnt(0)
	v_mfma_f32_16x16x32_bf16 v[124:127], v[128:131], v[160:163], v[124:127]
	v_mfma_f32_16x16x32_bf16 v[124:127], v[132:135], v[164:167], v[124:127]
	v_mfma_f32_16x16x32_bf16 v[120:123], v[136:139], v[160:163], v[120:123]
	v_mfma_f32_16x16x32_bf16 v[120:123], v[140:143], v[164:167], v[120:123]
	v_mfma_f32_16x16x32_bf16 v[108:111], v[128:131], v[190:193], v[108:111]
	v_mfma_f32_16x16x32_bf16 v[108:111], v[132:135], v[194:197], v[108:111]
	v_mfma_f32_16x16x32_bf16 v[104:107], v[136:139], v[190:193], v[104:107]
	v_mfma_f32_16x16x32_bf16 v[104:107], v[140:143], v[194:197], v[104:107]
	v_mfma_f32_16x16x32_bf16 v[92:95], v[128:131], v[198:201], v[92:95]
	v_mfma_f32_16x16x32_bf16 v[92:95], v[132:135], v[202:205], v[92:95]
	v_mfma_f32_16x16x32_bf16 v[88:91], v[136:139], v[198:201], v[88:91]
	v_mfma_f32_16x16x32_bf16 v[88:91], v[140:143], v[202:205], v[88:91]
	v_mfma_f32_16x16x32_bf16 v[76:79], v[128:131], v[206:209], v[76:79]
	v_mfma_f32_16x16x32_bf16 v[76:79], v[132:135], v[210:213], v[76:79]
	v_mfma_f32_16x16x32_bf16 v[72:75], v[136:139], v[206:209], v[72:75]
	v_mfma_f32_16x16x32_bf16 v[72:75], v[140:143], v[210:213], v[72:75]
	s_setprio 0
	s_setprio 1
	v_mfma_f32_16x16x32_bf16 v[116:119], v[144:147], v[160:163], v[116:119]
	v_mfma_f32_16x16x32_bf16 v[116:119], v[148:151], v[164:167], v[116:119]
	v_mfma_f32_16x16x32_bf16 v[112:115], v[152:155], v[160:163], v[112:115]
	v_mfma_f32_16x16x32_bf16 v[112:115], v[156:159], v[164:167], v[112:115]
	v_mfma_f32_16x16x32_bf16 v[100:103], v[144:147], v[190:193], v[100:103]
	v_mfma_f32_16x16x32_bf16 v[100:103], v[148:151], v[194:197], v[100:103]
	v_mfma_f32_16x16x32_bf16 v[96:99], v[152:155], v[190:193], v[96:99]
	v_mfma_f32_16x16x32_bf16 v[96:99], v[156:159], v[194:197], v[96:99]
	v_mfma_f32_16x16x32_bf16 v[84:87], v[144:147], v[198:201], v[84:87]
	v_mfma_f32_16x16x32_bf16 v[84:87], v[148:151], v[202:205], v[84:87]
	v_mfma_f32_16x16x32_bf16 v[80:83], v[152:155], v[198:201], v[80:83]
	v_mfma_f32_16x16x32_bf16 v[80:83], v[156:159], v[202:205], v[80:83]
	v_mfma_f32_16x16x32_bf16 v[68:71], v[144:147], v[206:209], v[68:71]
	v_mfma_f32_16x16x32_bf16 v[68:71], v[148:151], v[210:213], v[68:71]
	v_mfma_f32_16x16x32_bf16 v[64:67], v[152:155], v[206:209], v[64:67]
	v_mfma_f32_16x16x32_bf16 v[64:67], v[156:159], v[210:213], v[64:67]
	s_setprio 0
	s_barrier
	s_add_i32 s36, s36, s43
	v_lshl_add_u64 v[214:215], s[34:35], 0, v[168:169]
	s_mov_b32 m0, s36
	ds_read_b128 v[160:163], v230 offset:16384
	ds_read_b128 v[164:167], v230 offset:17408
	ds_read_b128 v[190:193], v230 offset:18432
	ds_read_b128 v[194:197], v230 offset:19456
	ds_read_b128 v[198:201], v230 offset:20480
	ds_read_b128 v[202:205], v230 offset:21504
	ds_read_b128 v[206:209], v230 offset:22528
	ds_read_b128 v[210:213], v230 offset:23552
	global_load_lds_dwordx4 v[214:215], off
	s_add_i32 m0, s36, 0x2000
	s_add_u32 s36, s34, 0x100000
	v_lshl_add_u64 v[232:233], s[34:35], 0, v[180:181]
	s_addc_u32 s37, s35, 0
	s_add_i32 s58, s58, s43
	global_load_lds_dwordx4 v[232:233], off
	v_lshl_add_u64 v[234:235], s[36:37], 0, v[168:169]
	s_mov_b32 m0, s58
	v_lshl_add_u64 v[236:237], s[40:41], 0, v[182:183]
	global_load_lds_dwordx4 v[234:235], off
	v_lshl_add_u64 v[234:235], s[36:37], 0, v[180:181]
	s_add_i32 m0, s58, 0x2000
	s_nop 0
	global_load_lds_dwordx4 v[234:235], off
	v_lshl_add_u64 v[234:235], s[40:41], 0, v[184:185]
	s_mov_b32 m0, s44
	s_nop 0
	global_load_lds_dwordx4 v[234:235], off
	s_mov_b32 m0, s45
	s_nop 0
	global_load_lds_dwordx4 v[236:237], off
	s_waitcnt vmcnt(8)
	s_waitcnt lgkmcnt(0)
	s_barrier
	s_setprio 1
	s_waitcnt lgkmcnt(0)
	v_mfma_f32_16x16x32_bf16 v[60:63], v[128:131], v[160:163], v[60:63]
	v_mfma_f32_16x16x32_bf16 v[60:63], v[132:135], v[164:167], v[60:63]
	v_mfma_f32_16x16x32_bf16 v[56:59], v[136:139], v[160:163], v[56:59]
	v_mfma_f32_16x16x32_bf16 v[56:59], v[140:143], v[164:167], v[56:59]
	v_mfma_f32_16x16x32_bf16 v[44:47], v[128:131], v[190:193], v[44:47]
	v_mfma_f32_16x16x32_bf16 v[44:47], v[132:135], v[194:197], v[44:47]
	v_mfma_f32_16x16x32_bf16 v[40:43], v[136:139], v[190:193], v[40:43]
	v_mfma_f32_16x16x32_bf16 v[40:43], v[140:143], v[194:197], v[40:43]
	v_mfma_f32_16x16x32_bf16 v[28:31], v[128:131], v[198:201], v[28:31]
	v_mfma_f32_16x16x32_bf16 v[28:31], v[132:135], v[202:205], v[28:31]
	v_mfma_f32_16x16x32_bf16 v[24:27], v[136:139], v[198:201], v[24:27]
	v_mfma_f32_16x16x32_bf16 v[24:27], v[140:143], v[202:205], v[24:27]
	v_mfma_f32_16x16x32_bf16 v[12:15], v[128:131], v[206:209], v[12:15]
	v_mfma_f32_16x16x32_bf16 v[12:15], v[132:135], v[210:213], v[12:15]
	v_mfma_f32_16x16x32_bf16 v[8:11], v[136:139], v[206:209], v[8:11]
	v_mfma_f32_16x16x32_bf16 v[8:11], v[140:143], v[210:213], v[8:11]
	s_setprio 0
	s_setprio 1
	v_mfma_f32_16x16x32_bf16 v[52:55], v[144:147], v[160:163], v[52:55]
	v_mfma_f32_16x16x32_bf16 v[52:55], v[148:151], v[164:167], v[52:55]
	v_mfma_f32_16x16x32_bf16 v[48:51], v[152:155], v[160:163], v[48:51]
	v_mfma_f32_16x16x32_bf16 v[48:51], v[156:159], v[164:167], v[48:51]
	v_mfma_f32_16x16x32_bf16 v[36:39], v[144:147], v[190:193], v[36:39]
	v_mfma_f32_16x16x32_bf16 v[36:39], v[148:151], v[194:197], v[36:39]
	v_mfma_f32_16x16x32_bf16 v[32:35], v[152:155], v[190:193], v[32:35]
	v_mfma_f32_16x16x32_bf16 v[32:35], v[156:159], v[194:197], v[32:35]
	v_mfma_f32_16x16x32_bf16 v[20:23], v[144:147], v[198:201], v[20:23]
	v_mfma_f32_16x16x32_bf16 v[20:23], v[148:151], v[202:205], v[20:23]
	v_mfma_f32_16x16x32_bf16 v[16:19], v[152:155], v[198:201], v[16:19]
	v_mfma_f32_16x16x32_bf16 v[16:19], v[156:159], v[202:205], v[16:19]
	v_mfma_f32_16x16x32_bf16 v[4:7], v[144:147], v[206:209], v[4:7]
	v_mfma_f32_16x16x32_bf16 v[4:7], v[148:151], v[210:213], v[4:7]
	v_mfma_f32_16x16x32_bf16 v[0:3], v[152:155], v[206:209], v[0:3]
	v_mfma_f32_16x16x32_bf16 v[0:3], v[156:159], v[210:213], v[0:3]
	s_setprio 0
	s_barrier
	s_add_i32 s58, 0, 0x18000
	s_add_i32 s59, 0, 0x1c000
	v_add_u32_e32 v140, s58, v228
	v_add_u32_e32 v156, s59, v228
	ds_read_b128 v[128:131], v140
	ds_read_b128 v[132:135], v140 offset:1024
	ds_read_b128 v[136:139], v140 offset:2048
	ds_read_b128 v[140:143], v140 offset:3072
	ds_read_b128 v[144:147], v156
	ds_read_b128 v[148:151], v156 offset:1024
	ds_read_b128 v[152:155], v156 offset:2048
	ds_read_b128 v[156:159], v156 offset:3072
	s_add_u32 s36, s40, 0x100000
	s_addc_u32 s37, s41, 0
	s_mov_b32 m0, s46
	v_lshl_add_u64 v[238:239], s[36:37], 0, v[184:185]
	ds_read_b128 v[160:163], v230 offset:32768
	ds_read_b128 v[164:167], v230 offset:33792
	ds_read_b128 v[190:193], v230 offset:34816
	ds_read_b128 v[194:197], v230 offset:35840
	ds_read_b128 v[198:201], v230 offset:36864
	ds_read_b128 v[202:205], v230 offset:37888
	ds_read_b128 v[206:209], v230 offset:38912
	ds_read_b128 v[210:213], v230 offset:39936
	global_load_lds_dwordx4 v[238:239], off
	v_lshl_add_u64 v[238:239], s[36:37], 0, v[182:183]
	s_mov_b32 m0, s47
	s_nop 0
	global_load_lds_dwordx4 v[238:239], off
	s_waitcnt vmcnt(8)
	s_waitcnt lgkmcnt(0)
	s_barrier
	s_setprio 1
	s_waitcnt lgkmcnt(0)
	v_mfma_f32_16x16x32_bf16 v[124:127], v[128:131], v[160:163], v[124:127]
	v_mfma_f32_16x16x32_bf16 v[124:127], v[132:135], v[164:167], v[124:127]
	v_mfma_f32_16x16x32_bf16 v[120:123], v[136:139], v[160:163], v[120:123]
	v_mfma_f32_16x16x32_bf16 v[120:123], v[140:143], v[164:167], v[120:123]
	v_mfma_f32_16x16x32_bf16 v[108:111], v[128:131], v[190:193], v[108:111]
	v_mfma_f32_16x16x32_bf16 v[108:111], v[132:135], v[194:197], v[108:111]
	v_mfma_f32_16x16x32_bf16 v[104:107], v[136:139], v[190:193], v[104:107]
	v_mfma_f32_16x16x32_bf16 v[104:107], v[140:143], v[194:197], v[104:107]
	v_mfma_f32_16x16x32_bf16 v[92:95], v[128:131], v[198:201], v[92:95]
	v_mfma_f32_16x16x32_bf16 v[92:95], v[132:135], v[202:205], v[92:95]
	v_mfma_f32_16x16x32_bf16 v[88:91], v[136:139], v[198:201], v[88:91]
	v_mfma_f32_16x16x32_bf16 v[88:91], v[140:143], v[202:205], v[88:91]
	v_mfma_f32_16x16x32_bf16 v[76:79], v[128:131], v[206:209], v[76:79]
	v_mfma_f32_16x16x32_bf16 v[76:79], v[132:135], v[210:213], v[76:79]
	v_mfma_f32_16x16x32_bf16 v[72:75], v[136:139], v[206:209], v[72:75]
	v_mfma_f32_16x16x32_bf16 v[72:75], v[140:143], v[210:213], v[72:75]
	s_setprio 0
	s_setprio 1
	v_mfma_f32_16x16x32_bf16 v[116:119], v[144:147], v[160:163], v[116:119]
	v_mfma_f32_16x16x32_bf16 v[116:119], v[148:151], v[164:167], v[116:119]
	v_mfma_f32_16x16x32_bf16 v[112:115], v[152:155], v[160:163], v[112:115]
	v_mfma_f32_16x16x32_bf16 v[112:115], v[156:159], v[164:167], v[112:115]
	v_mfma_f32_16x16x32_bf16 v[100:103], v[144:147], v[190:193], v[100:103]
	v_mfma_f32_16x16x32_bf16 v[100:103], v[148:151], v[194:197], v[100:103]
	v_mfma_f32_16x16x32_bf16 v[96:99], v[152:155], v[190:193], v[96:99]
	v_mfma_f32_16x16x32_bf16 v[96:99], v[156:159], v[194:197], v[96:99]
	v_mfma_f32_16x16x32_bf16 v[84:87], v[144:147], v[198:201], v[84:87]
	v_mfma_f32_16x16x32_bf16 v[84:87], v[148:151], v[202:205], v[84:87]
	v_mfma_f32_16x16x32_bf16 v[80:83], v[152:155], v[198:201], v[80:83]
	v_mfma_f32_16x16x32_bf16 v[80:83], v[156:159], v[202:205], v[80:83]
	v_mfma_f32_16x16x32_bf16 v[68:71], v[144:147], v[206:209], v[68:71]
	v_mfma_f32_16x16x32_bf16 v[68:71], v[148:151], v[210:213], v[68:71]
	v_mfma_f32_16x16x32_bf16 v[64:67], v[152:155], v[206:209], v[64:67]
	v_mfma_f32_16x16x32_bf16 v[64:67], v[156:159], v[210:213], v[64:67]
	s_setprio 0
	s_barrier
	s_add_i32 s36, s58, s43
	v_lshl_add_u64 v[214:215], v[214:215], 0, s[20:21]
	s_mov_b32 m0, s36
	ds_read_b128 v[160:163], v230 offset:49152
	ds_read_b128 v[164:167], v230 offset:50176
	ds_read_b128 v[190:193], v230 offset:51200
	ds_read_b128 v[194:197], v230 offset:52224
	ds_read_b128 v[198:201], v230 offset:53248
	ds_read_b128 v[202:205], v230 offset:54272
	ds_read_b128 v[206:209], v230 offset:55296
	ds_read_b128 v[210:213], v230 offset:56320
	global_load_lds_dwordx4 v[214:215], off
	s_add_i32 m0, s36, 0x2000
	s_add_u32 s34, s34, 0x100080
	v_lshl_add_u64 v[214:215], v[232:233], 0, s[20:21]
	s_addc_u32 s35, s35, 0
	s_add_i32 s36, s59, s43
	global_load_lds_dwordx4 v[214:215], off
	v_lshl_add_u64 v[214:215], s[34:35], 0, v[168:169]
	s_mov_b32 m0, s36
	s_nop 0
	global_load_lds_dwordx4 v[214:215], off
	v_lshl_add_u64 v[214:215], s[34:35], 0, v[180:181]
	s_add_i32 m0, s36, 0x2000
	s_nop 0
	global_load_lds_dwordx4 v[214:215], off
	v_lshl_add_u64 v[214:215], v[234:235], 0, s[20:21]
	s_mov_b32 m0, s50
	s_nop 0
	global_load_lds_dwordx4 v[214:215], off
	v_lshl_add_u64 v[214:215], v[236:237], 0, s[20:21]
	s_mov_b32 m0, s51
	s_nop 0
	global_load_lds_dwordx4 v[214:215], off
	s_waitcnt vmcnt(8)
	s_waitcnt lgkmcnt(0)
	s_barrier
	s_setprio 1
	s_waitcnt lgkmcnt(0)
	v_mfma_f32_16x16x32_bf16 v[60:63], v[128:131], v[160:163], v[60:63]
	v_mfma_f32_16x16x32_bf16 v[60:63], v[132:135], v[164:167], v[60:63]
	v_mfma_f32_16x16x32_bf16 v[56:59], v[136:139], v[160:163], v[56:59]
	v_mfma_f32_16x16x32_bf16 v[56:59], v[140:143], v[164:167], v[56:59]
	v_mfma_f32_16x16x32_bf16 v[44:47], v[128:131], v[190:193], v[44:47]
	v_mfma_f32_16x16x32_bf16 v[44:47], v[132:135], v[194:197], v[44:47]
	v_mfma_f32_16x16x32_bf16 v[40:43], v[136:139], v[190:193], v[40:43]
	v_mfma_f32_16x16x32_bf16 v[40:43], v[140:143], v[194:197], v[40:43]
	v_mfma_f32_16x16x32_bf16 v[28:31], v[128:131], v[198:201], v[28:31]
	v_mfma_f32_16x16x32_bf16 v[28:31], v[132:135], v[202:205], v[28:31]
	v_mfma_f32_16x16x32_bf16 v[24:27], v[136:139], v[198:201], v[24:27]
	v_mfma_f32_16x16x32_bf16 v[24:27], v[140:143], v[202:205], v[24:27]
	v_mfma_f32_16x16x32_bf16 v[12:15], v[128:131], v[206:209], v[12:15]
	v_mfma_f32_16x16x32_bf16 v[12:15], v[132:135], v[210:213], v[12:15]
	v_mfma_f32_16x16x32_bf16 v[8:11], v[136:139], v[206:209], v[8:11]
	v_mfma_f32_16x16x32_bf16 v[8:11], v[140:143], v[210:213], v[8:11]
	s_setprio 0
	s_setprio 1
	v_mfma_f32_16x16x32_bf16 v[52:55], v[144:147], v[160:163], v[52:55]
	v_mfma_f32_16x16x32_bf16 v[52:55], v[148:151], v[164:167], v[52:55]
	v_mfma_f32_16x16x32_bf16 v[48:51], v[152:155], v[160:163], v[48:51]
	v_mfma_f32_16x16x32_bf16 v[48:51], v[156:159], v[164:167], v[48:51]
	v_mfma_f32_16x16x32_bf16 v[36:39], v[144:147], v[190:193], v[36:39]
	v_mfma_f32_16x16x32_bf16 v[36:39], v[148:151], v[194:197], v[36:39]
	v_mfma_f32_16x16x32_bf16 v[32:35], v[152:155], v[190:193], v[32:35]
	v_mfma_f32_16x16x32_bf16 v[32:35], v[156:159], v[194:197], v[32:35]
	v_mfma_f32_16x16x32_bf16 v[20:23], v[144:147], v[198:201], v[20:23]
	v_mfma_f32_16x16x32_bf16 v[20:23], v[148:151], v[202:205], v[20:23]
	v_mfma_f32_16x16x32_bf16 v[16:19], v[152:155], v[198:201], v[16:19]
	v_mfma_f32_16x16x32_bf16 v[16:19], v[156:159], v[202:205], v[16:19]
	v_mfma_f32_16x16x32_bf16 v[4:7], v[144:147], v[206:209], v[4:7]
	v_mfma_f32_16x16x32_bf16 v[4:7], v[148:151], v[210:213], v[4:7]
	v_mfma_f32_16x16x32_bf16 v[0:3], v[152:155], v[206:209], v[0:3]
	v_mfma_f32_16x16x32_bf16 v[0:3], v[156:159], v[210:213], v[0:3]
	s_setprio 0
	s_barrier
	s_add_i32 s57, s57, 2
	s_add_u32 s8, s8, 0x100
	s_addc_u32 s9, s9, 0
	s_add_u32 s55, s55, 0x100
	s_addc_u32 s56, s56, 0
	s_cmp_gt_u32 s57, 61
	s_cbranch_scc0 .LBB0_986
	s_and_b64 vcc, exec, s[12:13]
	s_cbranch_vccz .LBB0_989
	s_barrier
